# XCD-aware attention item remap (K/V shared in one XCD L2) + scan chunk-top vmcnt no longer waits for y stores
# speedup vs baseline: 1.0102x; 1.0102x over previous
; DI unsigned pk2(float lo, float hi) { f32x2 v = {lo, hi}; bf16x2_t b = __builtin_convertvector(v, bf16x2_t); return __builtin_bit_cast(unsigned, b); }
; DI void scan_phase(PPtr p, int j, ldsp lds, int tid, int wave, int lane) {
;     ...
;         for (int c = 0; c < 32; ++c) {
;             const int t0 = b * SEQ + c * 128;
;             {
;                 const float x0 = dr0 + dtb, x1 = dr1 + dtb;
;                 const float d0 = x0 > 20.f ? x0 : log1pf(__expf(x0)), d1 = x1 > 20.f ? x1 : log1pf(__expf(x1));
;     ...
;                 bf16_t* yp = Y + (size_t)(t0 + l) * DIN + h * 64 + ph * 32 + 4 * hi;
; #pragma unroll
;                 for (int gq = 0; gq < 4; ++gq) { u32x2 w; w.x = pk2(ya[4 * gq], ya[4 * gq + 1]); w.y = pk2(ya[4 * gq + 2], ya[4 * gq + 3]); *(u32x2*)(yp + 8 * gq) = w; }
.LBB0_649:
	v_lshl_add_u32 v2, s18, 7, v237
	v_ashrrev_i32_e32 v3, 31, v2
	v_lshlrev_b64 v[2:3], 12, v[2:3]
	v_lshl_add_u64 v[2:3], v[162:163], 0, v[2:3]
	v_cvt_pk_bf16_f32 v4, v32, v33
	v_cvt_pk_bf16_f32 v5, v34, v35
	global_store_dwordx2 v[2:3], v[4:5], off
	v_cvt_pk_bf16_f32 v4, v36, v37
	v_cvt_pk_bf16_f32 v5, v38, v39
	global_store_dwordx2 v[2:3], v[4:5], off offset:16
	v_cvt_pk_bf16_f32 v4, v40, v41
	v_cvt_pk_bf16_f32 v5, v42, v43
	global_store_dwordx2 v[2:3], v[4:5], off offset:32
	v_cvt_pk_bf16_f32 v4, v44, v45
	v_cvt_pk_bf16_f32 v5, v46, v47
	global_store_dwordx2 v[2:3], v[4:5], off offset:48
	s_cmp_eq_u32 s19, 32
	s_mov_b32 s18, s19
	s_cbranch_scc1 .LBB0_639
	s_waitcnt vmcnt(4)
	s_branch .Lscan_chunk_body
.LBB0_650:
	s_cmp_eq_u32 s19, 32
	s_mov_b32 s18, s19
	s_cbranch_scc1 .LBB0_639
.LBB0_651:
	s_waitcnt vmcnt(0)
.Lscan_chunk_body:
	v_add_f32_e32 v0, v234, v238
	s_mov_b32 s19, 0x41a00000
	v_cmp_nlt_f32_e32 vcc, s19, v0
	s_and_saveexec_b64 s[98:99], vcc
	s_cbranch_execz .LBB0_653
	v_mul_f32_e32 v0, 0x3fb8aa3b, v0
	v_exp_f32_e32 v0, v0
	s_mov_b32 s19, 0x3f2aaaab
	v_add_f32_e32 v4, 1.0, v0
	v_frexp_mant_f32_e32 v6, v4
	v_cvt_f64_f32_e32 v[2:3], v4
	v_frexp_exp_i32_f64_e32 v2, v[2:3]
	v_cmp_gt_f32_e32 vcc, s19, v6
	v_add_f32_e32 v5, -1.0, v4
	v_sub_f32_e32 v7, v5, v4
	v_subbrev_co_u32_e32 v10, vcc, 0, v2, vcc
	v_sub_u32_e32 v2, 0, v10
	v_sub_f32_e32 v5, v0, v5
	v_add_f32_e32 v7, 1.0, v7
	v_ldexp_f32 v3, v4, v2
	v_add_f32_e32 v5, v5, v7
	v_add_f32_e32 v4, -1.0, v3
	v_add_f32_e32 v6, 1.0, v3
	v_ldexp_f32 v2, v5, v2
	v_add_f32_e32 v5, 1.0, v4
	v_add_f32_e32 v7, -1.0, v6
	v_sub_f32_e32 v5, v3, v5
	v_sub_f32_e32 v3, v3, v7
	v_add_f32_e32 v5, v2, v5
	v_add_f32_e32 v2, v2, v3
	v_add_f32_e32 v11, v6, v2
	v_rcp_f32_e32 v13, v11
	v_sub_f32_e32 v3, v11, v6
	v_sub_f32_e32 v12, v2, v3
	v_add_f32_e32 v3, v4, v5
	v_mul_f32_e32 v15, v3, v13
	v_sub_f32_e32 v2, v3, v4
	v_mul_f32_e32 v4, v11, v15
	v_fma_f32 v6, v15, v11, -v4
	v_fmac_f32_e32 v6, v15, v12
	v_sub_f32_e32 v14, v5, v2
	v_add_f32_e32 v2, v4, v6
	v_sub_f32_e32 v5, v3, v2
	v_pk_add_f32 v[8:9], v[2:3], v[4:5] neg_lo:[0,1] neg_hi:[0,1]
	v_mov_b32_e32 v7, v2
	v_pk_add_f32 v[2:3], v[8:9], v[6:7] neg_lo:[0,1] neg_hi:[0,1]
	s_mov_b32 s19, 0x3f317218
	v_add_f32_e32 v3, v14, v3
	v_add_f32_e32 v2, v2, v3
	v_add_f32_e32 v3, v5, v2
	v_mul_f32_e32 v14, v13, v3
	v_mul_f32_e32 v4, v11, v14
	v_fma_f32 v6, v14, v11, -v4
	v_fmac_f32_e32 v6, v14, v12
	v_sub_f32_e32 v5, v5, v3
	v_add_f32_e32 v11, v2, v5
	v_add_f32_e32 v2, v4, v6
	v_sub_f32_e32 v5, v3, v2
	v_pk_add_f32 v[8:9], v[2:3], v[4:5] neg_lo:[0,1] neg_hi:[0,1]
	v_mov_b32_e32 v7, v2
	v_pk_add_f32 v[2:3], v[8:9], v[6:7] neg_lo:[0,1] neg_hi:[0,1]
	s_nop 0
	v_add_f32_e32 v3, v11, v3
	v_add_f32_e32 v2, v2, v3
	v_add_f32_e32 v3, v15, v14
	v_add_f32_e32 v2, v5, v2
	v_sub_f32_e32 v4, v3, v15
	v_mul_f32_e32 v2, v13, v2
	v_sub_f32_e32 v4, v14, v4
	v_add_f32_e32 v4, v4, v2
	v_add_f32_e32 v6, v3, v4
	v_mul_f32_e32 v7, v6, v6
	v_fmamk_f32 v2, v7, 0x3e9b6dac, v205
	v_fmaak_f32 v155, v7, v2, 0x3f2aaada
	v_cvt_f32_i32_e32 v2, v10
	v_sub_f32_e32 v3, v6, v3
	v_sub_f32_e32 v3, v4, v3
	v_ldexp_f32 v8, v3, 1
	v_mul_f32_e32 v3, v6, v7
	v_ldexp_f32 v5, v6, 1
	v_pk_mul_f32 v[6:7], v[2:3], v[154:155]
	s_nop 0
	v_fma_f32 v4, v2, s19, -v6
	v_fmac_f32_e32 v4, 0xb102e308, v2
	v_pk_add_f32 v[2:3], v[6:7], v[4:5]
	s_mov_b32 s19, 0x7f800000
	v_sub_f32_e32 v5, v3, v5
	v_sub_f32_e32 v5, v7, v5
	v_add_f32_e32 v9, v8, v5
	v_mov_b32_e32 v8, v6
	v_pk_add_f32 v[6:7], v[2:3], v[6:7] neg_lo:[0,1] neg_hi:[0,1]
	v_pk_add_f32 v[10:11], v[2:3], v[8:9]
	v_mov_b32_e32 v5, v2
	v_mov_b32_e32 v7, v11
	v_pk_add_f32 v[12:13], v[4:5], v[6:7] neg_lo:[0,1] neg_hi:[0,1]
	v_pk_add_f32 v[4:5], v[4:5], v[6:7]
	v_mov_b32_e32 v8, v9
	v_pk_add_f32 v[6:7], v[4:5], v[2:3] op_sel:[1,0] op_sel_hi:[0,1] neg_lo:[0,1] neg_hi:[0,1]
	v_pk_add_f32 v[14:15], v[10:11], v[6:7] op_sel_hi:[1,0] neg_lo:[0,1] neg_hi:[0,1]
	v_mov_b32_e32 v10, v11
	v_mov_b32_e32 v11, v5
	v_pk_mov_b32 v[6:7], v[2:3], v[6:7] op_sel:[1,0]
	v_mov_b32_e32 v9, v2
	v_pk_add_f32 v[6:7], v[10:11], v[6:7] neg_lo:[0,1] neg_hi:[0,1]
	v_mov_b32_e32 v14, v12
	v_pk_add_f32 v[2:3], v[8:9], v[6:7] neg_lo:[0,1] neg_hi:[0,1]
	v_mov_b32_e32 v13, v5
	v_pk_add_f32 v[6:7], v[14:15], v[2:3]
	v_cmp_neq_f32_e32 vcc, s19, v0
	v_pk_add_f32 v[8:9], v[6:7], v[6:7] op_sel:[0,1] op_sel_hi:[1,0]
	s_mov_b32 s19, 0x33800000
	v_pk_add_f32 v[4:5], v[4:5], v[8:9] op_sel:[1,0] op_sel_hi:[0,1]
	v_mov_b32_e32 v7, v4
	v_pk_add_f32 v[10:11], v[6:7], v[12:13] neg_lo:[0,1] neg_hi:[0,1]
	v_mov_b32_e32 v3, v8
	v_sub_f32_e32 v5, v6, v10
	v_pk_add_f32 v[2:3], v[2:3], v[10:11] neg_lo:[0,1] neg_hi:[0,1]
	v_sub_f32_e32 v5, v12, v5
	v_add_f32_e32 v2, v2, v5
	v_add_f32_e32 v2, v2, v3
	v_add_f32_e32 v2, v4, v2
	v_cndmask_b32_e32 v2, v215, v2, vcc
	v_cmp_ngt_f32_e32 vcc, -1.0, v0
	s_nop 1
	v_cndmask_b32_e32 v2, v216, v2, vcc
	v_cmp_neq_f32_e32 vcc, -1.0, v0
	s_nop 1
	v_cndmask_b32_e32 v2, v217, v2, vcc
	v_cmp_lt_f32_e64 vcc, |v0|, s19
	s_nop 1
	v_cndmask_b32_e32 v0, v2, v0, vcc
; DI void scan_phase(PPtr p, int j, ldsp lds, int tid, int wave, int lane) {
;     ...
;                 const float x0 = dr0 + dtb, x1 = dr1 + dtb;
;                 const float d0 = x0 > 20.f ? x0 : log1pf(__expf(x0)), d1 = x1 > 20.f ? x1 : log1pf(__expf(x1));
.LBB0_653:
	s_or_b64 exec, exec, s[98:99]
	s_waitcnt vmcnt(4)
	v_add_f32_e32 v2, v234, v239
	s_mov_b32 s19, 0x41a00000
	v_cmp_nlt_f32_e32 vcc, s19, v2
	s_and_saveexec_b64 s[98:99], vcc
	s_cbranch_execz .LBB0_655
	v_mul_f32_e32 v2, 0x3fb8aa3b, v2
	v_exp_f32_e32 v32, v2
	s_mov_b32 s19, 0x3f2aaaab
	v_add_f32_e32 v4, 1.0, v32
	v_frexp_mant_f32_e32 v6, v4
	v_cvt_f64_f32_e32 v[2:3], v4
	v_frexp_exp_i32_f64_e32 v2, v[2:3]
	v_cmp_gt_f32_e32 vcc, s19, v6
	v_add_f32_e32 v5, -1.0, v4
	v_sub_f32_e32 v7, v5, v4
	v_subbrev_co_u32_e32 v10, vcc, 0, v2, vcc
	v_sub_u32_e32 v2, 0, v10
	v_sub_f32_e32 v5, v32, v5
	v_add_f32_e32 v7, 1.0, v7
	v_ldexp_f32 v3, v4, v2
	v_add_f32_e32 v5, v5, v7
	v_add_f32_e32 v4, -1.0, v3
	v_add_f32_e32 v6, 1.0, v3
	v_ldexp_f32 v2, v5, v2
	v_add_f32_e32 v5, 1.0, v4
	v_add_f32_e32 v7, -1.0, v6
	v_sub_f32_e32 v5, v3, v5
	v_sub_f32_e32 v3, v3, v7
	v_add_f32_e32 v5, v2, v5
	v_add_f32_e32 v2, v2, v3
	v_add_f32_e32 v11, v6, v2
	v_rcp_f32_e32 v13, v11
	v_sub_f32_e32 v3, v11, v6
	v_sub_f32_e32 v12, v2, v3
	v_add_f32_e32 v3, v4, v5
	v_mul_f32_e32 v15, v3, v13
	v_sub_f32_e32 v2, v3, v4
	v_mul_f32_e32 v4, v11, v15
	v_fma_f32 v6, v15, v11, -v4
	v_fmac_f32_e32 v6, v15, v12
	v_sub_f32_e32 v14, v5, v2
	v_add_f32_e32 v2, v4, v6
	v_sub_f32_e32 v5, v3, v2
	v_pk_add_f32 v[8:9], v[2:3], v[4:5] neg_lo:[0,1] neg_hi:[0,1]
	v_mov_b32_e32 v7, v2
	v_pk_add_f32 v[2:3], v[8:9], v[6:7] neg_lo:[0,1] neg_hi:[0,1]
	s_mov_b32 s19, 0x3f317218
	v_add_f32_e32 v3, v14, v3
	v_add_f32_e32 v2, v2, v3
	v_add_f32_e32 v3, v5, v2
	v_mul_f32_e32 v14, v13, v3
	v_mul_f32_e32 v4, v11, v14
	v_fma_f32 v6, v14, v11, -v4
	v_fmac_f32_e32 v6, v14, v12
	v_sub_f32_e32 v5, v5, v3
	v_add_f32_e32 v11, v2, v5
	v_add_f32_e32 v2, v4, v6
	v_sub_f32_e32 v5, v3, v2
	v_pk_add_f32 v[8:9], v[2:3], v[4:5] neg_lo:[0,1] neg_hi:[0,1]
	v_mov_b32_e32 v7, v2
	v_pk_add_f32 v[2:3], v[8:9], v[6:7] neg_lo:[0,1] neg_hi:[0,1]
	s_nop 0
	v_add_f32_e32 v3, v11, v3
	v_add_f32_e32 v2, v2, v3
	v_add_f32_e32 v3, v15, v14
	v_add_f32_e32 v2, v5, v2
	v_sub_f32_e32 v4, v3, v15
	v_mul_f32_e32 v2, v13, v2
	v_sub_f32_e32 v4, v14, v4
	v_add_f32_e32 v4, v4, v2
	v_add_f32_e32 v6, v3, v4
	v_mul_f32_e32 v7, v6, v6
	v_fmamk_f32 v2, v7, 0x3e9b6dac, v205
	v_fmaak_f32 v155, v7, v2, 0x3f2aaada
	v_cvt_f32_i32_e32 v2, v10
	v_sub_f32_e32 v3, v6, v3
	v_sub_f32_e32 v3, v4, v3
	v_ldexp_f32 v8, v3, 1
	v_mul_f32_e32 v3, v6, v7
	v_ldexp_f32 v5, v6, 1
	v_pk_mul_f32 v[6:7], v[2:3], v[154:155]
	s_nop 0
	v_fma_f32 v4, v2, s19, -v6
	v_fmac_f32_e32 v4, 0xb102e308, v2
	v_pk_add_f32 v[2:3], v[6:7], v[4:5]
	s_mov_b32 s19, 0x7f800000
	v_sub_f32_e32 v5, v3, v5
	v_sub_f32_e32 v5, v7, v5
	v_add_f32_e32 v9, v8, v5
	v_mov_b32_e32 v8, v6
	v_pk_add_f32 v[6:7], v[2:3], v[6:7] neg_lo:[0,1] neg_hi:[0,1]
	v_pk_add_f32 v[10:11], v[2:3], v[8:9]
	v_mov_b32_e32 v5, v2
	v_mov_b32_e32 v7, v11
	v_pk_add_f32 v[12:13], v[4:5], v[6:7] neg_lo:[0,1] neg_hi:[0,1]
	v_pk_add_f32 v[4:5], v[4:5], v[6:7]
	v_mov_b32_e32 v8, v9
	v_pk_add_f32 v[6:7], v[4:5], v[2:3] op_sel:[1,0] op_sel_hi:[0,1] neg_lo:[0,1] neg_hi:[0,1]
	v_pk_add_f32 v[14:15], v[10:11], v[6:7] op_sel_hi:[1,0] neg_lo:[0,1] neg_hi:[0,1]
	v_mov_b32_e32 v10, v11
	v_mov_b32_e32 v11, v5
	v_pk_mov_b32 v[6:7], v[2:3], v[6:7] op_sel:[1,0]
	v_mov_b32_e32 v9, v2
	v_pk_add_f32 v[6:7], v[10:11], v[6:7] neg_lo:[0,1] neg_hi:[0,1]
	v_mov_b32_e32 v14, v12
	v_pk_add_f32 v[2:3], v[8:9], v[6:7] neg_lo:[0,1] neg_hi:[0,1]
	v_mov_b32_e32 v13, v5
	v_pk_add_f32 v[6:7], v[14:15], v[2:3]
	v_cmp_neq_f32_e32 vcc, s19, v32
	v_pk_add_f32 v[8:9], v[6:7], v[6:7] op_sel:[0,1] op_sel_hi:[1,0]
	s_mov_b32 s19, 0x33800000
	v_pk_add_f32 v[4:5], v[4:5], v[8:9] op_sel:[1,0] op_sel_hi:[0,1]
	v_mov_b32_e32 v7, v4
	v_pk_add_f32 v[10:11], v[6:7], v[12:13] neg_lo:[0,1] neg_hi:[0,1]
	v_mov_b32_e32 v3, v8
	v_sub_f32_e32 v5, v6, v10
	v_pk_add_f32 v[2:3], v[2:3], v[10:11] neg_lo:[0,1] neg_hi:[0,1]
	v_sub_f32_e32 v5, v12, v5
	v_add_f32_e32 v2, v2, v5
	v_add_f32_e32 v2, v2, v3
	v_add_f32_e32 v2, v4, v2
	v_cndmask_b32_e32 v2, v215, v2, vcc
	v_cmp_ngt_f32_e32 vcc, -1.0, v32
	s_nop 1
	v_cndmask_b32_e32 v2, v216, v2, vcc
	v_cmp_neq_f32_e32 vcc, -1.0, v32
	s_nop 1
	v_cndmask_b32_e32 v2, v217, v2, vcc
	v_cmp_lt_f32_e64 vcc, |v32|, s19
	s_nop 1
	v_cndmask_b32_e32 v2, v2, v32, vcc

; DI void attn_phase(PPtr p, int j, ldsp lds, int tid, int wave, int lane) {
;     ...
;     for (int item = blockIdx.x; item < 512; item += gridDim.x) {
;         const int bh = item >> 3, jj = item & 7, b = bh >> 4, hd = bh & 15;
;         const bf16_t* kbase = Kb + ((size_t)b * SEQ * HEADS + hd) * QKH;
;         const bf16_t* vbase = Vt + ((size_t)(b * HEADS + hd) * 64) * SEQ;
.LBB0_848:
	s_cmpk_lg_u32 s90, 0x100
	s_mov_b32 s6, s11
	s_cbranch_scc1 .Lattn_noremap
	s_lshr_b32 s2, s11, 8
	s_and_b32 s3, s11, 7
	s_bfe_u32 s4, s11, 0x50003
	s_lshl_b32 s2, s2, 5
	s_lshl_b32 s3, s3, 2
	s_add_i32 s2, s2, s3
	s_lshr_b32 s3, s4, 3
	s_add_i32 s2, s2, s3
	s_and_b32 s4, s4, 7
	s_lshl_b32 s2, s2, 3
	s_or_b32 s6, s2, s4
.Lattn_noremap:
	s_ashr_i32 s2, s6, 7
	s_ashr_i32 s3, s2, 31
	s_bfe_u32 s12, s6, 0x40003
	s_lshl_b64 s[4:5], s[2:3], 16
	s_or_b32 s3, s4, s12
	s_mul_i32 s4, s5, 0xc0
	s_mul_hi_u32 s5, s3, 0xc0
	s_and_b32 s13, s6, 7
	s_add_i32 s5, s5, s4
	s_mulk_i32 s3, 0xc0
	s_add_u32 s4, s8, s3
	s_addc_u32 s5, s9, s5
	s_lshl_b32 s3, s2, 4
	s_or_b32 s6, s3, s12
	s_mul_i32 s16, s12, 0xc0
	s_ashr_i32 s7, s6, 31
	s_lshl_b32 s15, s2, 12
	v_lshl_add_u64 v[2:3], s[4:5], 0, v[160:161]
	s_mul_hi_i32 s3, s2, 0xc00000
	s_mul_i32 s2, s2, 0xc00000
	s_lshl_b64 s[6:7], s[6:7], 19
	v_lshl_add_u64 v[178:179], v[162:163], 1, v[2:3]
	s_lshl_b32 s96, s12, 7
	v_lshl_add_u64 v[2:3], s[4:5], 0, v[168:169]
	s_or_b32 s2, s2, s16
	s_xor_b32 s14, s13, 15
	v_lshl_add_u64 v[180:181], v[170:171], 0, s[6:7]
	v_lshl_add_u64 v[182:183], v[166:167], 0, s[96:97]
	v_lshl_add_u64 v[184:185], v[164:165], 1, v[2:3]
	v_lshl_add_u64 v[186:187], v[172:173], 0, s[2:3]
	v_lshl_add_u64 v[188:189], v[174:175], 0, s[6:7]
	v_lshl_add_u64 v[190:191], v[176:177], 0, s[2:3]
	s_mov_b64 s[4:5], -1
	s_branch .LBB0_850

;     DI void operator()(f32x4 (&acc)[2][2][4][2], const Unit& u, int wr, int wc, int fr, int fq) const {
;         const int col0 = u.pn * BM + wc * 32 + 4 * fq; const float* g = gate + (size_t)(u.pm >> 4) * 9216;
;         {
;             f32x4 gv[2][2];
; #pragma unroll
;             for (int bj = 0; bj < 2; ++bj)
; #pragma unroll
;                 for (int n = 0; n < 2; ++n) gv[bj][n] = *(const f32x4*)(g + col0 + bj * HALF + n * 16) * gs;
; #pragma unroll
;             for (int ai = 0; ai < 2; ++ai)
; #pragma unroll
;                 for (int m = 0; m < 4; ++m) { const int row = u.pm * BM + ai * HALF + wr * 64 + m * 16 + fr; const size_t off = (size_t)row * DM + col0;
;                     float sq = 0.f;
; #pragma unroll
;                     for (int bj = 0; bj < 2; ++bj)
; #pragma unroll
;                         for (int n = 0; n < 2; ++n) { const f32x4 xi = *(const f32x4*)(xin + off + bj * HALF + n * 16);
;                             const f32x4 o = xi + gv[bj][n] * acc[ai][bj][m][n];
;                             if (!fused) *(f32x4*)(xout + off + bj * HALF + n * 16) = o;
;                             acc[ai][bj][m][n] = o;
;                             sq += (o[0] * o[0] + o[1] * o[1]) + (o[2] * o[2] + o[3] * o[3]); }
.LBB0_948:
	s_ashr_i32 s20, s42, 4
	s_mul_hi_i32 s21, s20, 0x9000
	s_mul_i32 s20, s20, 0x9000
	v_lshl_or_b32 v136, s43, 8, v146
	s_add_u32 s20, s33, s20
	s_addc_u32 s21, s34, s21
	v_ashrrev_i32_e32 v137, 31, v136
	v_lshl_add_u32 v138, s42, 8, v144
	v_lshl_add_u64 v[140:141], v[136:137], 2, s[20:21]
	v_ashrrev_i32_e32 v139, 31, v138
	global_load_dwordx4 v[148:151], v[140:141], off
	v_lshlrev_b64 v[142:143], 10, v[138:139]
	v_lshl_add_u64 v[142:143], v[142:143], 0, v[136:137]
	v_readlane_b32 s20, v254, 61
	v_lshlrev_b64 v[142:143], 2, v[142:143]
	v_readlane_b32 s21, v254, 62
	v_lshl_add_u64 v[174:175], s[10:11], 0, v[142:143]
	s_and_b64 vcc, exec, s[4:5]
	v_lshl_add_u64 v[172:173], s[20:21], 0, v[142:143]
	global_load_dwordx4 v[156:159], v[172:173], off
	global_load_dwordx4 v[160:163], v[140:141], off offset:64
	global_load_dwordx4 v[164:167], v[140:141], off offset:512
	global_load_dwordx4 v[168:171], v[140:141], off offset:576
	s_mov_b64 s[4:5], -1
	s_waitcnt vmcnt(0)
	v_pk_mul_f32 v[140:141], s[16:17], v[150:151]
	v_pk_mul_f32 v[142:143], s[8:9], v[148:149]
	v_pk_fma_f32 v[128:129], v[128:129], v[140:141], v[158:159]
	v_pk_fma_f32 v[126:127], v[126:127], v[142:143], v[156:157]
	global_store_dwordx4 v[174:175], v[126:129], off
	global_load_dwordx4 v[148:151], v[172:173], off offset:64
	s_nop 0
	v_pk_mul_f32 v[126:127], s[16:17], v[162:163]
	v_pk_mul_f32 v[128:129], s[8:9], v[160:161]
	s_waitcnt vmcnt(0)
	v_pk_fma_f32 v[124:125], v[124:125], v[126:127], v[150:151]
	v_pk_fma_f32 v[122:123], v[122:123], v[128:129], v[148:149]
	global_store_dwordx4 v[174:175], v[122:125], off offset:64
	global_load_dwordx4 v[148:151], v[172:173], off offset:512
	s_nop 0
	v_pk_mul_f32 v[122:123], s[16:17], v[166:167]
	v_pk_mul_f32 v[124:125], s[8:9], v[164:165]
	s_waitcnt vmcnt(0)
	v_pk_fma_f32 v[120:121], v[120:121], v[122:123], v[150:151]
	v_pk_fma_f32 v[118:119], v[118:119], v[124:125], v[148:149]
	global_store_dwordx4 v[174:175], v[118:121], off offset:512
	global_load_dwordx4 v[148:151], v[172:173], off offset:576
	s_nop 0
	v_or_b32_e32 v118, 16, v138
	v_ashrrev_i32_e32 v119, 31, v118
	v_lshlrev_b64 v[118:119], 10, v[118:119]
	v_lshl_add_u64 v[118:119], v[118:119], 0, v[136:137]
	v_lshlrev_b64 v[156:157], 2, v[118:119]
	v_pk_mul_f32 v[118:119], s[16:17], v[170:171]
	v_pk_mul_f32 v[120:121], s[8:9], v[168:169]
	v_lshl_add_u64 v[158:159], s[20:21], 0, v[156:157]
	s_waitcnt vmcnt(0)
	v_pk_fma_f32 v[108:109], v[108:109], v[118:119], v[150:151]
	v_pk_fma_f32 v[106:107], v[106:107], v[120:121], v[148:149]
	global_store_dwordx4 v[174:175], v[106:109], off offset:576
	global_load_dwordx4 v[106:109], v[158:159], off
	v_lshl_add_u64 v[148:149], s[10:11], 0, v[156:157]
	s_waitcnt vmcnt(0)
	v_pk_fma_f32 v[108:109], v[116:117], v[140:141], v[108:109]
	v_pk_fma_f32 v[106:107], v[114:115], v[142:143], v[106:107]
	global_store_dwordx4 v[148:149], v[106:109], off
	global_load_dwordx4 v[106:109], v[158:159], off offset:64
	s_waitcnt vmcnt(0)
	v_pk_fma_f32 v[108:109], v[112:113], v[126:127], v[108:109]
	v_pk_fma_f32 v[106:107], v[110:111], v[128:129], v[106:107]
	global_store_dwordx4 v[148:149], v[106:109], off offset:64
	global_load_dwordx4 v[106:109], v[158:159], off offset:512
	s_waitcnt vmcnt(0)
	v_pk_fma_f32 v[104:105], v[104:105], v[122:123], v[108:109]
	v_pk_fma_f32 v[102:103], v[102:103], v[124:125], v[106:107]
	global_store_dwordx4 v[148:149], v[102:105], off offset:512
	global_load_dwordx4 v[102:105], v[158:159], off offset:576
	v_or_b32_e32 v106, 32, v138
	v_ashrrev_i32_e32 v107, 31, v106
	v_lshlrev_b64 v[106:107], 10, v[106:107]
	v_lshl_add_u64 v[106:107], v[106:107], 0, v[136:137]
	v_lshlrev_b64 v[106:107], 2, v[106:107]
	v_lshl_add_u64 v[108:109], s[20:21], 0, v[106:107]
	s_waitcnt vmcnt(0)
	v_pk_fma_f32 v[92:93], v[92:93], v[118:119], v[104:105]
	v_pk_fma_f32 v[90:91], v[90:91], v[120:121], v[102:103]
	global_store_dwordx4 v[148:149], v[90:93], off offset:576
	global_load_dwordx4 v[90:93], v[108:109], off
	v_lshl_add_u64 v[102:103], s[10:11], 0, v[106:107]
	s_waitcnt vmcnt(0)
	v_pk_fma_f32 v[92:93], v[100:101], v[140:141], v[92:93]
	v_pk_fma_f32 v[90:91], v[98:99], v[142:143], v[90:91]
	global_store_dwordx4 v[102:103], v[90:93], off
	global_load_dwordx4 v[90:93], v[108:109], off offset:64
	s_waitcnt vmcnt(0)
	v_pk_fma_f32 v[92:93], v[96:97], v[126:127], v[92:93]
	v_pk_fma_f32 v[90:91], v[94:95], v[128:129], v[90:91]
	global_store_dwordx4 v[102:103], v[90:93], off offset:64
	global_load_dwordx4 v[90:93], v[108:109], off offset:512
	s_waitcnt vmcnt(0)
	v_pk_fma_f32 v[88:89], v[88:89], v[122:123], v[92:93]
	v_pk_fma_f32 v[86:87], v[86:87], v[124:125], v[90:91]
	global_store_dwordx4 v[102:103], v[86:89], off offset:512
	global_load_dwordx4 v[86:89], v[108:109], off offset:576
	v_or_b32_e32 v90, 48, v138
	v_ashrrev_i32_e32 v91, 31, v90
	v_lshlrev_b64 v[90:91], 10, v[90:91]
	v_lshl_add_u64 v[90:91], v[90:91], 0, v[136:137]
	v_lshlrev_b64 v[90:91], 2, v[90:91]
	v_lshl_add_u64 v[92:93], s[20:21], 0, v[90:91]
	s_waitcnt vmcnt(0)
	v_pk_fma_f32 v[76:77], v[76:77], v[118:119], v[88:89]
	v_pk_fma_f32 v[74:75], v[74:75], v[120:121], v[86:87]
	global_store_dwordx4 v[102:103], v[74:77], off offset:576
	global_load_dwordx4 v[74:77], v[92:93], off
	v_lshl_add_u64 v[86:87], s[10:11], 0, v[90:91]
	s_waitcnt vmcnt(0)
	v_pk_fma_f32 v[76:77], v[84:85], v[140:141], v[76:77]
	v_pk_fma_f32 v[74:75], v[82:83], v[142:143], v[74:75]
	global_store_dwordx4 v[86:87], v[74:77], off
	global_load_dwordx4 v[74:77], v[92:93], off offset:64
	s_waitcnt vmcnt(0)
;     DI void operator()(f32x4 (&acc)[2][2][4][2], const Unit& u, int wr, int wc, int fr, int fq) const {
;     ...
;                 for (int m = 0; m < 4; ++m) { const int row = u.pm * BM + ai * HALF + wr * 64 + m * 16 + fr; const size_t off = (size_t)row * DM + col0;
;                     float sq = 0.f;
; #pragma unroll
;                     for (int bj = 0; bj < 2; ++bj)
; #pragma unroll
;                         for (int n = 0; n < 2; ++n) { const f32x4 xi = *(const f32x4*)(xin + off + bj * HALF + n * 16);
;                             const f32x4 o = xi + gv[bj][n] * acc[ai][bj][m][n];
;                             if (!fused) *(f32x4*)(xout + off + bj * HALF + n * 16) = o;
;                             acc[ai][bj][m][n] = o;
;                             sq += (o[0] * o[0] + o[1] * o[1]) + (o[2] * o[2] + o[3] * o[3]); }
	v_pk_fma_f32 v[76:77], v[80:81], v[126:127], v[76:77]
	v_pk_fma_f32 v[74:75], v[78:79], v[128:129], v[74:75]
	global_store_dwordx4 v[86:87], v[74:77], off offset:64
	global_load_dwordx4 v[74:77], v[92:93], off offset:512
	s_waitcnt vmcnt(0)
	v_pk_fma_f32 v[72:73], v[72:73], v[122:123], v[76:77]
	v_pk_fma_f32 v[70:71], v[70:71], v[124:125], v[74:75]
	global_store_dwordx4 v[86:87], v[70:73], off offset:512
	global_load_dwordx4 v[70:73], v[92:93], off offset:576
	v_add_u32_e32 v74, 0x80, v138
	v_ashrrev_i32_e32 v75, 31, v74
	v_lshlrev_b64 v[74:75], 10, v[74:75]
	v_lshl_add_u64 v[74:75], v[74:75], 0, v[136:137]
	v_lshlrev_b64 v[74:75], 2, v[74:75]
	v_lshl_add_u64 v[76:77], s[20:21], 0, v[74:75]
	s_waitcnt vmcnt(0)
	v_pk_fma_f32 v[68:69], v[68:69], v[118:119], v[72:73]
	v_pk_fma_f32 v[66:67], v[66:67], v[120:121], v[70:71]
	global_store_dwordx4 v[86:87], v[66:69], off offset:576
	global_load_dwordx4 v[66:69], v[76:77], off
	v_lshl_add_u64 v[70:71], s[10:11], 0, v[74:75]
	s_waitcnt vmcnt(0)
	v_pk_fma_f32 v[64:65], v[64:65], v[140:141], v[68:69]
	v_pk_fma_f32 v[62:63], v[62:63], v[142:143], v[66:67]
	global_store_dwordx4 v[70:71], v[62:65], off
	global_load_dwordx4 v[62:65], v[76:77], off offset:64
	s_waitcnt vmcnt(0)
	v_pk_fma_f32 v[60:61], v[60:61], v[126:127], v[64:65]
	v_pk_fma_f32 v[58:59], v[58:59], v[128:129], v[62:63]
	global_store_dwordx4 v[70:71], v[58:61], off offset:64
	global_load_dwordx4 v[58:61], v[76:77], off offset:512
	s_waitcnt vmcnt(0)
	v_pk_fma_f32 v[56:57], v[56:57], v[122:123], v[60:61]
	v_pk_fma_f32 v[54:55], v[54:55], v[124:125], v[58:59]
	global_store_dwordx4 v[70:71], v[54:57], off offset:512
	global_load_dwordx4 v[54:57], v[76:77], off offset:576
	v_add_u32_e32 v58, 0x90, v138
	v_ashrrev_i32_e32 v59, 31, v58
	v_lshlrev_b64 v[58:59], 10, v[58:59]
	v_lshl_add_u64 v[58:59], v[58:59], 0, v[136:137]
	v_lshlrev_b64 v[58:59], 2, v[58:59]
	v_lshl_add_u64 v[60:61], s[20:21], 0, v[58:59]
	s_waitcnt vmcnt(0)
	v_pk_fma_f32 v[44:45], v[44:45], v[118:119], v[56:57]
	v_pk_fma_f32 v[42:43], v[42:43], v[120:121], v[54:55]
	global_store_dwordx4 v[70:71], v[42:45], off offset:576
	global_load_dwordx4 v[42:45], v[60:61], off
	v_lshl_add_u64 v[54:55], s[10:11], 0, v[58:59]
	s_waitcnt vmcnt(0)
	v_pk_fma_f32 v[44:45], v[52:53], v[140:141], v[44:45]
	v_pk_fma_f32 v[42:43], v[50:51], v[142:143], v[42:43]
	global_store_dwordx4 v[54:55], v[42:45], off
	global_load_dwordx4 v[42:45], v[60:61], off offset:64
	s_waitcnt vmcnt(0)
	v_pk_fma_f32 v[44:45], v[48:49], v[126:127], v[44:45]
	v_pk_fma_f32 v[42:43], v[46:47], v[128:129], v[42:43]
	global_store_dwordx4 v[54:55], v[42:45], off offset:64
	global_load_dwordx4 v[42:45], v[60:61], off offset:512
	s_waitcnt vmcnt(0)
	v_pk_fma_f32 v[40:41], v[40:41], v[122:123], v[44:45]
	v_pk_fma_f32 v[38:39], v[38:39], v[124:125], v[42:43]
	global_store_dwordx4 v[54:55], v[38:41], off offset:512
	global_load_dwordx4 v[38:41], v[60:61], off offset:576
	v_add_u32_e32 v42, 0xa0, v138
	v_ashrrev_i32_e32 v43, 31, v42
	v_lshlrev_b64 v[42:43], 10, v[42:43]
	v_lshl_add_u64 v[42:43], v[42:43], 0, v[136:137]
	v_lshlrev_b64 v[42:43], 2, v[42:43]
	v_lshl_add_u64 v[44:45], s[20:21], 0, v[42:43]
	s_waitcnt vmcnt(0)
	v_pk_fma_f32 v[28:29], v[28:29], v[118:119], v[40:41]
	v_pk_fma_f32 v[26:27], v[26:27], v[120:121], v[38:39]
	global_store_dwordx4 v[54:55], v[26:29], off offset:576
	global_load_dwordx4 v[26:29], v[44:45], off
	v_lshl_add_u64 v[38:39], s[10:11], 0, v[42:43]
	s_waitcnt vmcnt(0)
	v_pk_fma_f32 v[28:29], v[36:37], v[140:141], v[28:29]
	v_pk_fma_f32 v[26:27], v[34:35], v[142:143], v[26:27]
	global_store_dwordx4 v[38:39], v[26:29], off
	global_load_dwordx4 v[26:29], v[44:45], off offset:64
	s_waitcnt vmcnt(0)
	v_pk_fma_f32 v[28:29], v[32:33], v[126:127], v[28:29]
	v_pk_fma_f32 v[26:27], v[30:31], v[128:129], v[26:27]
	global_store_dwordx4 v[38:39], v[26:29], off offset:64
	global_load_dwordx4 v[26:29], v[44:45], off offset:512
	s_waitcnt vmcnt(0)
	v_pk_fma_f32 v[24:25], v[24:25], v[122:123], v[28:29]
	v_pk_fma_f32 v[22:23], v[22:23], v[124:125], v[26:27]
	global_store_dwordx4 v[38:39], v[22:25], off offset:512
	global_load_dwordx4 v[22:25], v[44:45], off offset:576
	v_add_u32_e32 v26, 0xb0, v138
	v_ashrrev_i32_e32 v27, 31, v26
	v_lshlrev_b64 v[26:27], 10, v[26:27]
	v_lshl_add_u64 v[26:27], v[26:27], 0, v[136:137]
	v_lshlrev_b64 v[26:27], 2, v[26:27]
	v_lshl_add_u64 v[28:29], s[20:21], 0, v[26:27]
	s_waitcnt vmcnt(0)
	v_pk_fma_f32 v[12:13], v[12:13], v[118:119], v[24:25]
	v_pk_fma_f32 v[10:11], v[10:11], v[120:121], v[22:23]
	global_store_dwordx4 v[38:39], v[10:13], off offset:576
	global_load_dwordx4 v[10:13], v[28:29], off
	v_lshl_add_u64 v[22:23], s[10:11], 0, v[26:27]
	s_waitcnt vmcnt(0)
	v_pk_fma_f32 v[12:13], v[20:21], v[140:141], v[12:13]
	v_pk_fma_f32 v[10:11], v[18:19], v[142:143], v[10:11]
	global_store_dwordx4 v[22:23], v[10:13], off
	global_load_dwordx4 v[10:13], v[28:29], off offset:64
	s_waitcnt vmcnt(0)
	v_pk_fma_f32 v[12:13], v[16:17], v[126:127], v[12:13]
	v_pk_fma_f32 v[10:11], v[14:15], v[128:129], v[10:11]
	global_store_dwordx4 v[22:23], v[10:13], off offset:64
	global_load_dwordx4 v[10:13], v[28:29], off offset:512
	s_waitcnt vmcnt(0)
	v_pk_fma_f32 v[8:9], v[8:9], v[122:123], v[12:13]
	v_pk_fma_f32 v[6:7], v[6:7], v[124:125], v[10:11]
	global_store_dwordx4 v[22:23], v[6:9], off offset:512
	global_load_dwordx4 v[6:9], v[28:29], off offset:576
	s_waitcnt vmcnt(0)
	v_pk_fma_f32 v[4:5], v[4:5], v[118:119], v[8:9]
	v_pk_fma_f32 v[2:3], v[2:3], v[120:121], v[6:7]
	global_store_dwordx4 v[22:23], v[2:5], off offset:576
	s_cbranch_vccnz .LBB0_933
	s_andn2_b64 vcc, exec, s[12:13]
	s_cbranch_vccnz .LBB0_932
	s_barrier
	s_branch .LBB0_932
